# MLA loop: barrier-phased schedule, plain softmax phase with its temporaries moved to free registers v218-249, next MFMA phase's address setup and first fragment reads issued before the softmax phase
# baseline (speedup 1.0000x reference)
.Lmv_pre_top:
	v_exp_f32_e32 v218, v66
	v_exp_f32_e32 v234, v50
	v_exp_f32_e32 v219, v67
	v_exp_f32_e32 v235, v51
	v_exp_f32_e32 v220, v68
	v_add_f32_e32 v155, v218, v219
	v_exp_f32_e32 v236, v52
	v_add_f32_e32 v156, v234, v235
	v_exp_f32_e32 v221, v69
	v_add_f32_e32 v155, v220, v155
	v_exp_f32_e32 v237, v53
	v_add_f32_e32 v156, v236, v156
	v_exp_f32_e32 v222, v70
	v_add_f32_e32 v155, v221, v155
	v_exp_f32_e32 v238, v54
	v_add_f32_e32 v156, v237, v156
	v_exp_f32_e32 v223, v71
	v_add_f32_e32 v155, v222, v155
	v_exp_f32_e32 v239, v55
	v_add_f32_e32 v156, v238, v156
	v_exp_f32_e32 v224, v72
	v_add_f32_e32 v155, v223, v155
	v_exp_f32_e32 v240, v56
	v_add_f32_e32 v156, v239, v156
	v_exp_f32_e32 v225, v73
	v_add_f32_e32 v155, v224, v155
	v_exp_f32_e32 v241, v57
	v_add_f32_e32 v156, v240, v156
	v_exp_f32_e32 v226, v74
	v_add_f32_e32 v155, v225, v155
	v_exp_f32_e32 v242, v58
	v_add_f32_e32 v156, v241, v156
	v_exp_f32_e32 v227, v75
	v_add_f32_e32 v155, v226, v155
	v_exp_f32_e32 v243, v59
	v_add_f32_e32 v156, v242, v156
	v_exp_f32_e32 v228, v76
	v_add_f32_e32 v155, v227, v155
	v_exp_f32_e32 v244, v60
	v_add_f32_e32 v156, v243, v156
	v_exp_f32_e32 v229, v77
	v_add_f32_e32 v155, v228, v155
	v_exp_f32_e32 v245, v61
	v_add_f32_e32 v156, v244, v156
	v_exp_f32_e32 v230, v78
	v_add_f32_e32 v155, v229, v155
	v_exp_f32_e32 v246, v62
	v_add_f32_e32 v156, v245, v156
	v_exp_f32_e32 v231, v79
	v_add_f32_e32 v155, v230, v155
	v_exp_f32_e32 v247, v63
	v_add_f32_e32 v156, v246, v156
	v_exp_f32_e32 v232, v80
	v_add_f32_e32 v155, v231, v155
	v_exp_f32_e32 v248, v64
	v_add_f32_e32 v156, v247, v156
	v_exp_f32_e32 v233, v81
	v_add_f32_e32 v155, v232, v155
	v_exp_f32_e32 v249, v65
	v_add_f32_e32 v156, v248, v156
	v_add_f32_e32 v155, v233, v155
	v_add_f32_e32 v156, v249, v156
	v_add_f32_e32 v157, v155, v156
	s_nop 0
	v_cmp_ngt_f32_e32 vcc, s72, v157
	s_nop 1
	s_or_b64 vcc, vcc, s[4:5]
	s_andn2_b64 vcc, vcc, s[10:11]
	s_cbranch_vccz .Lmv_pre_fast
	v_max3_f32 v154, v66, v67, v68
	v_max3_f32 v154, v154, v69, v70
	v_max3_f32 v154, v154, v71, v72
	v_max3_f32 v154, v154, v73, v74
	v_max3_f32 v154, v154, v75, v76
	v_max3_f32 v154, v154, v77, v78
	v_max3_f32 v154, v154, v79, v80
	v_max3_f32 v154, v154, v81, v50
	v_max3_f32 v154, v154, v51, v52
	v_max3_f32 v154, v154, v53, v54
	v_max3_f32 v154, v154, v55, v56
	v_max3_f32 v154, v154, v57, v58
	v_max3_f32 v154, v154, v59, v60
	v_max3_f32 v154, v154, v61, v62
	v_max3_f32 v154, v154, v63, v64
	v_max_f32_e32 v154, v154, v65
	ds_bpermute_b32 v148, v195, v154
	s_waitcnt lgkmcnt(0)
	v_max_f32_e32 v154, v154, v148
	s_and_b64 vcc, exec, s[4:5]
	s_cbranch_vccnz .Lmv_pre_anchor
	v_max_f32_e32 v154, 0, v154
	v_exp_f32_e64 v149, -v154
	s_nop 7
	s_nop 7
	v_mul_f32_e32 v183, v183, v149
	v_mul_f32_e32 v2, v2, v149
	v_mul_f32_e32 v3, v3, v149
	v_mul_f32_e32 v4, v4, v149
	v_mul_f32_e32 v5, v5, v149
	v_mul_f32_e32 v6, v6, v149
	v_mul_f32_e32 v7, v7, v149
	v_mul_f32_e32 v8, v8, v149
	v_mul_f32_e32 v9, v9, v149
	v_mul_f32_e32 v10, v10, v149
	v_mul_f32_e32 v11, v11, v149
	v_mul_f32_e32 v12, v12, v149
	v_mul_f32_e32 v13, v13, v149
	v_mul_f32_e32 v14, v14, v149
	v_mul_f32_e32 v15, v15, v149
	v_mul_f32_e32 v16, v16, v149
	v_mul_f32_e32 v17, v17, v149
	v_mul_f32_e32 v18, v18, v149
	v_mul_f32_e32 v19, v19, v149
	v_mul_f32_e32 v20, v20, v149
	v_mul_f32_e32 v21, v21, v149
	v_mul_f32_e32 v22, v22, v149
	v_mul_f32_e32 v23, v23, v149
	v_mul_f32_e32 v24, v24, v149
	v_mul_f32_e32 v25, v25, v149
	v_mul_f32_e32 v26, v26, v149
	v_mul_f32_e32 v27, v27, v149
	v_mul_f32_e32 v28, v28, v149
	v_mul_f32_e32 v29, v29, v149
	v_mul_f32_e32 v30, v30, v149
	v_mul_f32_e32 v31, v31, v149
	v_mul_f32_e32 v32, v32, v149
	v_mul_f32_e32 v33, v33, v149

.Lmv_pre_fast:
	v_cvt_pk_bf16_f32 v82, v218, v219
	v_cvt_pk_bf16_f32 v83, v220, v221
	v_cvt_pk_bf16_f32 v84, v222, v223
	v_cvt_pk_bf16_f32 v85, v224, v225
	v_cvt_pk_bf16_f32 v86, v226, v227
	v_cvt_pk_bf16_f32 v87, v228, v229
	v_cvt_pk_bf16_f32 v88, v230, v231
	v_cvt_pk_bf16_f32 v89, v232, v233
	v_cvt_pk_bf16_f32 v90, v234, v235
	v_cvt_pk_bf16_f32 v91, v236, v237
	v_cvt_pk_bf16_f32 v92, v238, v239
	v_cvt_pk_bf16_f32 v93, v240, v241
	v_cvt_pk_bf16_f32 v94, v242, v243
	v_cvt_pk_bf16_f32 v95, v244, v245
	v_cvt_pk_bf16_f32 v96, v246, v247
	v_cvt_pk_bf16_f32 v97, v248, v249
	v_add_f32_e32 v183, v183, v157

.Lmk_skip2:
	v_readlane_b32 s0, v252, 7
	s_cmpk_lt_u32 s0, 0x100
	s_cbranch_scc1 .Lmh0
	v_lshl_add_u32 v0, s12, 14, v159
	s_add_i32 s0, s35, 0xffffc000
	s_and_b32 s0, s0, 0x4000
	v_add_u32_e32 v154, s0, v190
	v_add_u32_e32 v210, v0, v184
	v_add_u32_e32 v211, v0, v185
	v_add_u32_e32 v212, v0, v186
	v_add_u32_e32 v213, v0, v187
	v_add_u32_e32 v214, v0, v188
	v_add_u32_e32 v215, v0, v189
	v_add_u32_e32 v216, v154, v191
	v_add_u32_e32 v217, v154, v192
	v_add_u32_e32 v196, v154, v193
	v_add_u32_e32 v197, v154, v194
	ds_read_b128 v[98:101], v210
	ds_read_b128 v[102:105], v210 offset:8192
	ds_read_b128 v[106:109], v211
	ds_read_b128 v[110:113], v211 offset:8192
	s_cmp_eq_u32 s36, 2
	s_cselect_b64 s[4:5], -1, 0
	s_mov_b64 s[10:11], 0

.Lmv_h1a_fast:
	v_cvt_pk_bf16_f32 v82, v218, v219
	v_cvt_pk_bf16_f32 v83, v220, v221
	v_cvt_pk_bf16_f32 v84, v222, v223
	v_cvt_pk_bf16_f32 v85, v224, v225
	v_cvt_pk_bf16_f32 v86, v226, v227
	v_cvt_pk_bf16_f32 v87, v228, v229
	v_cvt_pk_bf16_f32 v88, v230, v231
	v_cvt_pk_bf16_f32 v89, v232, v233
	v_cvt_pk_bf16_f32 v90, v234, v235
	v_cvt_pk_bf16_f32 v91, v236, v237
	v_cvt_pk_bf16_f32 v92, v238, v239
	v_cvt_pk_bf16_f32 v93, v240, v241
	v_cvt_pk_bf16_f32 v94, v242, v243
	v_cvt_pk_bf16_f32 v95, v244, v245
	v_cvt_pk_bf16_f32 v96, v246, v247
	v_cvt_pk_bf16_f32 v97, v248, v249
	v_add_f32_e32 v183, v183, v157
	s_barrier
	s_setprio 1
	s_waitcnt lgkmcnt(3)
	v_mfma_f32_32x32x16_bf16 v[66:81], v[98:101], v[114:117], v[34:49]
	ds_read_b128 v[98:101], v212
	s_waitcnt lgkmcnt(3)
	v_mfma_f32_32x32x16_bf16 v[50:65], v[102:105], v[114:117], v[34:49]
	ds_read_b128 v[102:105], v212 offset:8192
	s_waitcnt lgkmcnt(3)
	v_mfma_f32_32x32x16_bf16 v[66:81], v[106:109], v[118:121], v[66:81]
	ds_read_b128 v[106:109], v213
	s_waitcnt lgkmcnt(3)
	v_mfma_f32_32x32x16_bf16 v[50:65], v[110:113], v[118:121], v[50:65]
	ds_read_b128 v[110:113], v213 offset:8192
	s_waitcnt lgkmcnt(3)
	v_mfma_f32_32x32x16_bf16 v[66:81], v[98:101], v[122:125], v[66:81]
	ds_read_b128 v[98:101], v214
	s_waitcnt lgkmcnt(3)
	v_mfma_f32_32x32x16_bf16 v[50:65], v[102:105], v[122:125], v[50:65]
	ds_read_b128 v[102:105], v214 offset:8192
	s_waitcnt lgkmcnt(3)
	v_mfma_f32_32x32x16_bf16 v[66:81], v[106:109], v[126:129], v[66:81]
	ds_read_b128 v[106:109], v215
	s_waitcnt lgkmcnt(3)
	v_mfma_f32_32x32x16_bf16 v[50:65], v[110:113], v[126:129], v[50:65]
	ds_read_b128 v[110:113], v215 offset:8192
	s_waitcnt lgkmcnt(3)
	v_mfma_f32_32x32x16_bf16 v[66:81], v[98:101], v[130:133], v[66:81]
	ds_read_b128 v[98:101], v216
	s_waitcnt lgkmcnt(3)
	v_mfma_f32_32x32x16_bf16 v[50:65], v[102:105], v[130:133], v[50:65]
	ds_read_b128 v[102:105], v216 offset:4096
	s_waitcnt lgkmcnt(3)
	v_mfma_f32_32x32x16_bf16 v[66:81], v[106:109], v[134:137], v[66:81]
	ds_read_b128 v[106:109], v217
	s_waitcnt lgkmcnt(3)
	v_mfma_f32_32x32x16_bf16 v[50:65], v[110:113], v[134:137], v[50:65]
	ds_read_b128 v[110:113], v217 offset:4096
	s_waitcnt lgkmcnt(3)
	v_mfma_f32_32x32x16_bf16 v[2:17], v[98:101], v[82:85], v[2:17]
	ds_read_b128 v[98:101], v196
	s_waitcnt lgkmcnt(3)
	v_mfma_f32_32x32x16_bf16 v[18:33], v[102:105], v[82:85], v[18:33]
	ds_read_b128 v[102:105], v196 offset:4096
	s_waitcnt lgkmcnt(3)
	v_mfma_f32_32x32x16_bf16 v[2:17], v[106:109], v[86:89], v[2:17]
	ds_read_b128 v[106:109], v197
	s_waitcnt lgkmcnt(3)
	v_mfma_f32_32x32x16_bf16 v[18:33], v[110:113], v[86:89], v[18:33]
	ds_read_b128 v[110:113], v197 offset:4096
	s_waitcnt lgkmcnt(3)
	v_mfma_f32_32x32x16_bf16 v[2:17], v[98:101], v[90:93], v[2:17]
	s_waitcnt lgkmcnt(2)
	v_mfma_f32_32x32x16_bf16 v[18:33], v[102:105], v[90:93], v[18:33]
	s_waitcnt lgkmcnt(1)
	v_mfma_f32_32x32x16_bf16 v[2:17], v[106:109], v[94:97], v[2:17]
	s_waitcnt lgkmcnt(0)
	v_mfma_f32_32x32x16_bf16 v[18:33], v[110:113], v[94:97], v[18:33]
	s_setprio 0
	s_barrier
	s_cmp_ge_u32 s36, s34
	s_cbranch_scc1 .Lmv1_skip1
	s_and_b32 s0, s35, 0x4000
	s_add_i32 m0, s27, s0
	v_lshl_add_u64 v[198:199], s[84:85], 0, v[176:177]
	v_lshl_add_u64 v[198:199], v[198:199], 0, s[78:79]
	global_load_lds_dwordx4 v[198:199], off

.Lmv1_skip2:
	s_add_i32 s8, s8, 0x8000
	s_and_b32 s0, s8, 0x8000
	v_add_u32_e32 v0, s0, v159
	v_lshl_add_u32 v154, s12, 13, v190
	v_add_u32_e32 v210, v0, v184
	v_add_u32_e32 v211, v0, v185
	v_add_u32_e32 v212, v0, v186
	v_add_u32_e32 v213, v0, v187
	v_add_u32_e32 v214, v0, v188
	v_add_u32_e32 v215, v0, v189
	v_add_u32_e32 v216, v154, v191
	v_add_u32_e32 v217, v154, v192
	v_add_u32_e32 v196, v154, v193
	v_add_u32_e32 v197, v154, v194
	ds_read_b128 v[98:101], v210
	ds_read_b128 v[102:105], v210 offset:8192
	ds_read_b128 v[106:109], v211
	ds_read_b128 v[110:113], v211 offset:8192
	s_mov_b64 s[4:5], 0
	s_mov_b64 s[10:11], 0

.Lmv_h1b_fast:
	v_cvt_pk_bf16_f32 v82, v218, v219
	v_cvt_pk_bf16_f32 v83, v220, v221
	v_cvt_pk_bf16_f32 v84, v222, v223
	v_cvt_pk_bf16_f32 v85, v224, v225
	v_cvt_pk_bf16_f32 v86, v226, v227
	v_cvt_pk_bf16_f32 v87, v228, v229
	v_cvt_pk_bf16_f32 v88, v230, v231
	v_cvt_pk_bf16_f32 v89, v232, v233
	v_cvt_pk_bf16_f32 v90, v234, v235
	v_cvt_pk_bf16_f32 v91, v236, v237
	v_cvt_pk_bf16_f32 v92, v238, v239
	v_cvt_pk_bf16_f32 v93, v240, v241
	v_cvt_pk_bf16_f32 v94, v242, v243
	v_cvt_pk_bf16_f32 v95, v244, v245
	v_cvt_pk_bf16_f32 v96, v246, v247
	v_cvt_pk_bf16_f32 v97, v248, v249
	v_add_f32_e32 v183, v183, v157
	s_barrier
	s_setprio 1
	s_waitcnt lgkmcnt(3)
	v_mfma_f32_32x32x16_bf16 v[66:81], v[98:101], v[114:117], v[34:49]
	ds_read_b128 v[98:101], v212
	s_waitcnt lgkmcnt(3)
	v_mfma_f32_32x32x16_bf16 v[50:65], v[102:105], v[114:117], v[34:49]
	ds_read_b128 v[102:105], v212 offset:8192
	s_waitcnt lgkmcnt(3)
	v_mfma_f32_32x32x16_bf16 v[66:81], v[106:109], v[118:121], v[66:81]
	ds_read_b128 v[106:109], v213
	s_waitcnt lgkmcnt(3)
	v_mfma_f32_32x32x16_bf16 v[50:65], v[110:113], v[118:121], v[50:65]
	ds_read_b128 v[110:113], v213 offset:8192
	s_waitcnt lgkmcnt(3)
	v_mfma_f32_32x32x16_bf16 v[66:81], v[98:101], v[122:125], v[66:81]
	ds_read_b128 v[98:101], v214
	s_waitcnt lgkmcnt(3)
	v_mfma_f32_32x32x16_bf16 v[50:65], v[102:105], v[122:125], v[50:65]
	ds_read_b128 v[102:105], v214 offset:8192
	s_waitcnt lgkmcnt(3)
	v_mfma_f32_32x32x16_bf16 v[66:81], v[106:109], v[126:129], v[66:81]
	ds_read_b128 v[106:109], v215
	s_waitcnt lgkmcnt(3)
	v_mfma_f32_32x32x16_bf16 v[50:65], v[110:113], v[126:129], v[50:65]
	ds_read_b128 v[110:113], v215 offset:8192
	s_waitcnt lgkmcnt(3)
	v_mfma_f32_32x32x16_bf16 v[66:81], v[98:101], v[130:133], v[66:81]
	ds_read_b128 v[98:101], v216
	s_waitcnt lgkmcnt(3)
	v_mfma_f32_32x32x16_bf16 v[50:65], v[102:105], v[130:133], v[50:65]
	ds_read_b128 v[102:105], v216 offset:4096
	s_waitcnt lgkmcnt(3)
	v_mfma_f32_32x32x16_bf16 v[66:81], v[106:109], v[134:137], v[66:81]
	ds_read_b128 v[106:109], v217
	s_waitcnt lgkmcnt(3)
	v_mfma_f32_32x32x16_bf16 v[50:65], v[110:113], v[134:137], v[50:65]
	ds_read_b128 v[110:113], v217 offset:4096
	s_waitcnt lgkmcnt(3)
	v_mfma_f32_32x32x16_bf16 v[2:17], v[98:101], v[82:85], v[2:17]
	ds_read_b128 v[98:101], v196
	s_waitcnt lgkmcnt(3)
	v_mfma_f32_32x32x16_bf16 v[18:33], v[102:105], v[82:85], v[18:33]
	ds_read_b128 v[102:105], v196 offset:4096
	s_waitcnt lgkmcnt(3)
	v_mfma_f32_32x32x16_bf16 v[2:17], v[106:109], v[86:89], v[2:17]
	ds_read_b128 v[106:109], v197
	s_waitcnt lgkmcnt(3)
	v_mfma_f32_32x32x16_bf16 v[18:33], v[110:113], v[86:89], v[18:33]
	ds_read_b128 v[110:113], v197 offset:4096
	s_waitcnt lgkmcnt(3)
	v_mfma_f32_32x32x16_bf16 v[2:17], v[98:101], v[90:93], v[2:17]
	s_waitcnt lgkmcnt(2)
	v_mfma_f32_32x32x16_bf16 v[18:33], v[102:105], v[90:93], v[18:33]
	s_waitcnt lgkmcnt(1)
	v_mfma_f32_32x32x16_bf16 v[2:17], v[106:109], v[94:97], v[2:17]
	s_waitcnt lgkmcnt(0)
	v_mfma_f32_32x32x16_bf16 v[18:33], v[110:113], v[94:97], v[18:33]
	s_setprio 0
	s_branch .Lmjoin

.Lmv_h0a_fast:
	v_cvt_pk_bf16_f32 v82, v218, v219
	v_cvt_pk_bf16_f32 v83, v220, v221
	v_cvt_pk_bf16_f32 v84, v222, v223
	v_cvt_pk_bf16_f32 v85, v224, v225
	v_cvt_pk_bf16_f32 v86, v226, v227
	v_cvt_pk_bf16_f32 v87, v228, v229
	v_cvt_pk_bf16_f32 v88, v230, v231
	v_cvt_pk_bf16_f32 v89, v232, v233
	v_cvt_pk_bf16_f32 v90, v234, v235
	v_cvt_pk_bf16_f32 v91, v236, v237
	v_cvt_pk_bf16_f32 v92, v238, v239
	v_cvt_pk_bf16_f32 v93, v240, v241
	v_cvt_pk_bf16_f32 v94, v242, v243
	v_cvt_pk_bf16_f32 v95, v244, v245
	v_cvt_pk_bf16_f32 v96, v246, v247
	v_cvt_pk_bf16_f32 v97, v248, v249
	v_add_f32_e32 v183, v183, v157
	s_barrier
	s_setprio 1
	s_waitcnt lgkmcnt(3)
	v_mfma_f32_32x32x16_bf16 v[66:81], v[98:101], v[114:117], v[34:49]
	ds_read_b128 v[98:101], v212
	s_waitcnt lgkmcnt(3)
	v_mfma_f32_32x32x16_bf16 v[50:65], v[102:105], v[114:117], v[34:49]
	ds_read_b128 v[102:105], v212 offset:8192
	s_waitcnt lgkmcnt(3)
	v_mfma_f32_32x32x16_bf16 v[66:81], v[106:109], v[118:121], v[66:81]
	ds_read_b128 v[106:109], v213
	s_waitcnt lgkmcnt(3)
	v_mfma_f32_32x32x16_bf16 v[50:65], v[110:113], v[118:121], v[50:65]
	ds_read_b128 v[110:113], v213 offset:8192
	s_waitcnt lgkmcnt(3)
	v_mfma_f32_32x32x16_bf16 v[66:81], v[98:101], v[122:125], v[66:81]
	ds_read_b128 v[98:101], v214
	s_waitcnt lgkmcnt(3)
	v_mfma_f32_32x32x16_bf16 v[50:65], v[102:105], v[122:125], v[50:65]
	ds_read_b128 v[102:105], v214 offset:8192
	s_waitcnt lgkmcnt(3)
	v_mfma_f32_32x32x16_bf16 v[66:81], v[106:109], v[126:129], v[66:81]
	ds_read_b128 v[106:109], v215
	s_waitcnt lgkmcnt(3)
	v_mfma_f32_32x32x16_bf16 v[50:65], v[110:113], v[126:129], v[50:65]
	ds_read_b128 v[110:113], v215 offset:8192
	s_waitcnt lgkmcnt(3)
	v_mfma_f32_32x32x16_bf16 v[66:81], v[98:101], v[130:133], v[66:81]
	ds_read_b128 v[98:101], v216
	s_waitcnt lgkmcnt(3)
	v_mfma_f32_32x32x16_bf16 v[50:65], v[102:105], v[130:133], v[50:65]
	ds_read_b128 v[102:105], v216 offset:4096
	s_waitcnt lgkmcnt(3)
	v_mfma_f32_32x32x16_bf16 v[66:81], v[106:109], v[134:137], v[66:81]
	ds_read_b128 v[106:109], v217
	s_waitcnt lgkmcnt(3)
	v_mfma_f32_32x32x16_bf16 v[50:65], v[110:113], v[134:137], v[50:65]
	ds_read_b128 v[110:113], v217 offset:4096
	s_waitcnt lgkmcnt(3)
	v_mfma_f32_32x32x16_bf16 v[2:17], v[98:101], v[82:85], v[2:17]
	ds_read_b128 v[98:101], v196
	s_waitcnt lgkmcnt(3)
	v_mfma_f32_32x32x16_bf16 v[18:33], v[102:105], v[82:85], v[18:33]
	ds_read_b128 v[102:105], v196 offset:4096
	s_waitcnt lgkmcnt(3)
	v_mfma_f32_32x32x16_bf16 v[2:17], v[106:109], v[86:89], v[2:17]
	ds_read_b128 v[106:109], v197
	s_waitcnt lgkmcnt(3)
	v_mfma_f32_32x32x16_bf16 v[18:33], v[110:113], v[86:89], v[18:33]
	ds_read_b128 v[110:113], v197 offset:4096
	s_waitcnt lgkmcnt(3)
	v_mfma_f32_32x32x16_bf16 v[2:17], v[98:101], v[90:93], v[2:17]
	s_waitcnt lgkmcnt(2)
	v_mfma_f32_32x32x16_bf16 v[18:33], v[102:105], v[90:93], v[18:33]
	s_waitcnt lgkmcnt(1)
	v_mfma_f32_32x32x16_bf16 v[2:17], v[106:109], v[94:97], v[2:17]
	s_waitcnt lgkmcnt(0)
	v_mfma_f32_32x32x16_bf16 v[18:33], v[110:113], v[94:97], v[18:33]
	s_setprio 0
	s_barrier
	s_cmp_ge_u32 s36, s34
	s_cbranch_scc1 .Lmjoin
	s_mov_b64 s[4:5], 0
	s_mov_b64 s[10:11], 0
